# P5+P7 K-loop stage loads in saddr form (SGPR base + 32-bit VGPR offset, M0-compensated inst offset): 17 v_lshl_add_u64 per iteration removed
# speedup vs baseline: 1.0061x; 1.0012x over previous
.LBB0_639:
	s_add_i32 m0, s66, 0xc000
	ds_read_b128 v[52:55], v188
	ds_read_b128 v[56:59], v188 offset:1024
	ds_read_b128 v[60:63], v188 offset:2048
	ds_read_b128 v[64:67], v188 offset:3072
	ds_read_b128 v[72:75], v189
	ds_read_b128 v[76:79], v189 offset:1024
	ds_read_b128 v[80:83], v189 offset:2048
	ds_read_b128 v[84:87], v189 offset:3072
	s_add_u32 s60, s14, 0x1000
	s_addc_u32 s61, s15, 0
	s_cmp_eq_u32 s93, 60
	s_cselect_b32 s65, s11, s61
	s_cselect_b32 s64, s13, s60
	s_cselect_b32 s63, s53, s91
	s_cselect_b32 s62, s55, s90
	ds_read_b128 v[180:183], v190
	ds_read_b128 v[196:199], v190 offset:1024
	ds_read_b128 v[200:203], v190 offset:2048
	ds_read_b128 v[204:207], v190 offset:3072
	ds_read_b128 v[208:211], v190 offset:4096
	ds_read_b128 v[212:215], v190 offset:5120
	ds_read_b128 v[216:219], v190 offset:6144
	ds_read_b128 v[220:223], v190 offset:7168
	global_load_lds_dwordx4 v172, s[14:15]
	s_add_i32 m0, s66, 0xe000
	s_nop 0
	global_load_lds_dwordx4 v174, s[14:15]
	s_waitcnt vmcnt(8)
	s_waitcnt lgkmcnt(0)
	s_setprio 1
	s_barrier
	v_mfma_f32_16x16x32_bf16 v[156:159], v[52:55], v[180:183], v[156:159]
	v_mfma_f32_16x16x32_bf16 v[152:155], v[60:63], v[180:183], v[152:155]
	v_mfma_f32_16x16x32_bf16 v[140:143], v[52:55], v[200:203], v[140:143]
	v_mfma_f32_16x16x32_bf16 v[136:139], v[60:63], v[200:203], v[136:139]
	v_mfma_f32_16x16x32_bf16 v[124:127], v[52:55], v[208:211], v[124:127]
	v_mfma_f32_16x16x32_bf16 v[120:123], v[60:63], v[208:211], v[120:123]
	v_mfma_f32_16x16x32_bf16 v[108:111], v[52:55], v[216:219], v[108:111]
	v_mfma_f32_16x16x32_bf16 v[104:107], v[60:63], v[216:219], v[104:107]
	v_mfma_f32_16x16x32_bf16 v[156:159], v[56:59], v[196:199], v[156:159]
	v_mfma_f32_16x16x32_bf16 v[152:155], v[64:67], v[196:199], v[152:155]
	v_mfma_f32_16x16x32_bf16 v[140:143], v[56:59], v[204:207], v[140:143]
	v_mfma_f32_16x16x32_bf16 v[136:139], v[64:67], v[204:207], v[136:139]
	v_mfma_f32_16x16x32_bf16 v[124:127], v[56:59], v[212:215], v[124:127]
	v_mfma_f32_16x16x32_bf16 v[120:123], v[64:67], v[212:215], v[120:123]
	v_mfma_f32_16x16x32_bf16 v[108:111], v[56:59], v[220:223], v[108:111]
	v_mfma_f32_16x16x32_bf16 v[104:107], v[64:67], v[220:223], v[104:107]
	v_mfma_f32_16x16x32_bf16 v[144:147], v[72:75], v[180:183], v[144:147]
	v_mfma_f32_16x16x32_bf16 v[148:151], v[80:83], v[180:183], v[148:151]
	v_mfma_f32_16x16x32_bf16 v[128:131], v[72:75], v[200:203], v[128:131]
	v_mfma_f32_16x16x32_bf16 v[132:135], v[80:83], v[200:203], v[132:135]
	v_mfma_f32_16x16x32_bf16 v[112:115], v[72:75], v[208:211], v[112:115]
	v_mfma_f32_16x16x32_bf16 v[116:119], v[80:83], v[208:211], v[116:119]
	v_mfma_f32_16x16x32_bf16 v[96:99], v[72:75], v[216:219], v[96:99]
	v_mfma_f32_16x16x32_bf16 v[100:103], v[80:83], v[216:219], v[100:103]
	v_mfma_f32_16x16x32_bf16 v[144:147], v[76:79], v[196:199], v[144:147]
	v_mfma_f32_16x16x32_bf16 v[148:151], v[84:87], v[196:199], v[148:151]
	v_mfma_f32_16x16x32_bf16 v[128:131], v[76:79], v[204:207], v[128:131]
	v_mfma_f32_16x16x32_bf16 v[132:135], v[84:87], v[204:207], v[132:135]
	v_mfma_f32_16x16x32_bf16 v[112:115], v[76:79], v[212:215], v[112:115]
	v_mfma_f32_16x16x32_bf16 v[116:119], v[84:87], v[212:215], v[116:119]
	v_mfma_f32_16x16x32_bf16 v[96:99], v[76:79], v[220:223], v[96:99]
	v_mfma_f32_16x16x32_bf16 v[100:103], v[84:87], v[220:223], v[100:103]
	s_barrier
	s_setprio 0
	s_add_i32 s3, s80, s19
	s_mov_b32 m0, s3
	ds_read_b128 v[180:183], v190 offset:16384
	ds_read_b128 v[196:199], v190 offset:17408
	ds_read_b128 v[200:203], v190 offset:18432
	ds_read_b128 v[204:207], v190 offset:19456
	ds_read_b128 v[208:211], v190 offset:20480
	ds_read_b128 v[212:215], v190 offset:21504
	ds_read_b128 v[216:219], v190 offset:22528
	ds_read_b128 v[220:223], v190 offset:23552
	global_load_lds_dwordx4 v162, s[62:63]
	s_add_i32 m0, s3, 0x2000
	s_add_u32 s14, s62, 0x100000
	s_addc_u32 s15, s63, 0
	global_load_lds_dwordx4 v166, s[62:63]
	s_add_i32 s3, s81, s19
	s_mov_b32 m0, s3
	s_nop 0
	global_load_lds_dwordx4 v162, s[14:15]
	s_add_i32 m0, s3, 0x2000
	s_nop 0
	global_load_lds_dwordx4 v166, s[14:15]
	s_mov_b32 m0, s66
	s_nop 0
	global_load_lds_dwordx4 v160, s[64:65]
	s_mov_b32 m0, s67
	s_nop 0
	global_load_lds_dwordx4 v164, s[64:65]
	s_waitcnt vmcnt(8)
	s_waitcnt lgkmcnt(0)
	s_setprio 1
	s_barrier
	v_mfma_f32_16x16x32_bf16 v[92:95], v[52:55], v[180:183], v[92:95]
	v_mfma_f32_16x16x32_bf16 v[88:91], v[60:63], v[180:183], v[88:91]
	v_mfma_f32_16x16x32_bf16 v[44:47], v[52:55], v[200:203], v[44:47]
	v_mfma_f32_16x16x32_bf16 v[40:43], v[60:63], v[200:203], v[40:43]
	v_mfma_f32_16x16x32_bf16 v[28:31], v[52:55], v[208:211], v[28:31]
	v_mfma_f32_16x16x32_bf16 v[24:27], v[60:63], v[208:211], v[24:27]
	v_mfma_f32_16x16x32_bf16 v[12:15], v[52:55], v[216:219], v[12:15]
	v_mfma_f32_16x16x32_bf16 v[8:11], v[60:63], v[216:219], v[8:11]
	v_mfma_f32_16x16x32_bf16 v[92:95], v[56:59], v[196:199], v[92:95]
	v_mfma_f32_16x16x32_bf16 v[88:91], v[64:67], v[196:199], v[88:91]
	v_mfma_f32_16x16x32_bf16 v[44:47], v[56:59], v[204:207], v[44:47]
	v_mfma_f32_16x16x32_bf16 v[40:43], v[64:67], v[204:207], v[40:43]
	v_mfma_f32_16x16x32_bf16 v[28:31], v[56:59], v[212:215], v[28:31]
	v_mfma_f32_16x16x32_bf16 v[24:27], v[64:67], v[212:215], v[24:27]
	v_mfma_f32_16x16x32_bf16 v[12:15], v[56:59], v[220:223], v[12:15]
	v_mfma_f32_16x16x32_bf16 v[8:11], v[64:67], v[220:223], v[8:11]
	v_mfma_f32_16x16x32_bf16 v[48:51], v[72:75], v[180:183], v[48:51]
	v_mfma_f32_16x16x32_bf16 v[32:35], v[72:75], v[200:203], v[32:35]
	v_mfma_f32_16x16x32_bf16 v[36:39], v[80:83], v[200:203], v[36:39]
	v_mfma_f32_16x16x32_bf16 v[16:19], v[72:75], v[208:211], v[16:19]
	v_mfma_f32_16x16x32_bf16 v[20:23], v[80:83], v[208:211], v[20:23]
	v_mfma_f32_16x16x32_bf16 v[0:3], v[72:75], v[216:219], v[0:3]
	v_mfma_f32_16x16x32_bf16 v[4:7], v[80:83], v[216:219], v[4:7]
	v_mfma_f32_16x16x32_bf16 v[48:51], v[76:79], v[196:199], v[48:51]
	v_mfma_f32_16x16x32_bf16 v[52:55], v[80:83], v[180:183], v[68:71]
	v_mfma_f32_16x16x32_bf16 v[32:35], v[76:79], v[204:207], v[32:35]
	v_mfma_f32_16x16x32_bf16 v[36:39], v[84:87], v[204:207], v[36:39]
	v_mfma_f32_16x16x32_bf16 v[16:19], v[76:79], v[212:215], v[16:19]
	v_mfma_f32_16x16x32_bf16 v[20:23], v[84:87], v[212:215], v[20:23]
	v_mfma_f32_16x16x32_bf16 v[0:3], v[76:79], v[220:223], v[0:3]
	v_mfma_f32_16x16x32_bf16 v[4:7], v[84:87], v[220:223], v[4:7]
	v_mfma_f32_16x16x32_bf16 v[52:55], v[84:87], v[196:199], v[52:55]
	s_barrier
	s_setprio 0
	s_add_i32 s3, 0, 0x18000
	s_add_i32 s16, 0, 0x1c000
	v_add_u32_e32 v68, s3, v171
	v_add_u32_e32 v84, s16, v171
	s_add_u32 s14, s64, 0x80000
	s_addc_u32 s15, s65, 0
	s_mov_b32 m0, s70
	ds_read_b128 v[56:59], v68
	ds_read_b128 v[60:63], v68 offset:1024
	ds_read_b128 v[64:67], v68 offset:2048
	ds_read_b128 v[68:71], v68 offset:3072
	ds_read_b128 v[72:75], v84
	ds_read_b128 v[76:79], v84 offset:1024
	ds_read_b128 v[80:83], v84 offset:2048
	ds_read_b128 v[84:87], v84 offset:3072
	ds_read_b128 v[180:183], v190 offset:32768
	ds_read_b128 v[196:199], v190 offset:33792
	ds_read_b128 v[200:203], v190 offset:34816
	ds_read_b128 v[204:207], v190 offset:35840
	ds_read_b128 v[208:211], v190 offset:36864
	ds_read_b128 v[212:215], v190 offset:37888
	ds_read_b128 v[216:219], v190 offset:38912
	ds_read_b128 v[220:223], v190 offset:39936
	global_load_lds_dwordx4 v160, s[14:15]
	s_mov_b32 m0, s71
	s_nop 0
	global_load_lds_dwordx4 v164, s[14:15]
	s_waitcnt vmcnt(8)
	s_waitcnt lgkmcnt(0)
	s_setprio 1
	s_barrier
	v_mfma_f32_16x16x32_bf16 v[156:159], v[56:59], v[180:183], v[156:159]
	v_mfma_f32_16x16x32_bf16 v[152:155], v[64:67], v[180:183], v[152:155]
	v_mfma_f32_16x16x32_bf16 v[140:143], v[56:59], v[200:203], v[140:143]
	v_mfma_f32_16x16x32_bf16 v[136:139], v[64:67], v[200:203], v[136:139]
	v_mfma_f32_16x16x32_bf16 v[124:127], v[56:59], v[208:211], v[124:127]
	v_mfma_f32_16x16x32_bf16 v[120:123], v[64:67], v[208:211], v[120:123]
	v_mfma_f32_16x16x32_bf16 v[108:111], v[56:59], v[216:219], v[108:111]
	v_mfma_f32_16x16x32_bf16 v[104:107], v[64:67], v[216:219], v[104:107]
	v_mfma_f32_16x16x32_bf16 v[156:159], v[60:63], v[196:199], v[156:159]
	v_mfma_f32_16x16x32_bf16 v[152:155], v[68:71], v[196:199], v[152:155]
	v_mfma_f32_16x16x32_bf16 v[140:143], v[60:63], v[204:207], v[140:143]
	v_mfma_f32_16x16x32_bf16 v[136:139], v[68:71], v[204:207], v[136:139]
	v_mfma_f32_16x16x32_bf16 v[124:127], v[60:63], v[212:215], v[124:127]
	v_mfma_f32_16x16x32_bf16 v[120:123], v[68:71], v[212:215], v[120:123]
	v_mfma_f32_16x16x32_bf16 v[108:111], v[60:63], v[220:223], v[108:111]
	v_mfma_f32_16x16x32_bf16 v[104:107], v[68:71], v[220:223], v[104:107]
	v_mfma_f32_16x16x32_bf16 v[144:147], v[72:75], v[180:183], v[144:147]
	v_mfma_f32_16x16x32_bf16 v[148:151], v[80:83], v[180:183], v[148:151]
	v_mfma_f32_16x16x32_bf16 v[128:131], v[72:75], v[200:203], v[128:131]
	v_mfma_f32_16x16x32_bf16 v[132:135], v[80:83], v[200:203], v[132:135]
	v_mfma_f32_16x16x32_bf16 v[112:115], v[72:75], v[208:211], v[112:115]
	v_mfma_f32_16x16x32_bf16 v[116:119], v[80:83], v[208:211], v[116:119]
	v_mfma_f32_16x16x32_bf16 v[96:99], v[72:75], v[216:219], v[96:99]
	v_mfma_f32_16x16x32_bf16 v[100:103], v[80:83], v[216:219], v[100:103]
	v_mfma_f32_16x16x32_bf16 v[144:147], v[76:79], v[196:199], v[144:147]
	v_mfma_f32_16x16x32_bf16 v[148:151], v[84:87], v[196:199], v[148:151]
	v_mfma_f32_16x16x32_bf16 v[128:131], v[76:79], v[204:207], v[128:131]
	v_mfma_f32_16x16x32_bf16 v[132:135], v[84:87], v[204:207], v[132:135]
	v_mfma_f32_16x16x32_bf16 v[112:115], v[76:79], v[212:215], v[112:115]
	v_mfma_f32_16x16x32_bf16 v[116:119], v[84:87], v[212:215], v[116:119]
	v_mfma_f32_16x16x32_bf16 v[96:99], v[76:79], v[220:223], v[96:99]
	v_mfma_f32_16x16x32_bf16 v[100:103], v[84:87], v[220:223], v[100:103]
	s_barrier
	s_setprio 0
	s_add_i32 m0, s19, 0x17800
	ds_read_b128 v[180:183], v190 offset:49152
	ds_read_b128 v[196:199], v190 offset:50176
	ds_read_b128 v[200:203], v190 offset:51200
	ds_read_b128 v[204:207], v190 offset:52224
	ds_read_b128 v[208:211], v190 offset:53248
	ds_read_b128 v[212:215], v190 offset:54272
	ds_read_b128 v[216:219], v190 offset:55296
	ds_read_b128 v[220:223], v190 offset:56320
	global_load_lds_dwordx4 v162, s[62:63] offset:2048
	s_add_i32 m0, s19, 0x19800
	s_add_u32 s14, s62, 0x100800
	s_addc_u32 s15, s63, 0
	global_load_lds_dwordx4 v166, s[62:63] offset:2048
	s_add_i32 m0, s19, 0x1c000
	s_nop 0
	global_load_lds_dwordx4 v162, s[14:15]
	s_add_i32 m0, s19, 0x1e000
	s_nop 0
	global_load_lds_dwordx4 v166, s[14:15]
	s_add_i32 m0, s75, 0xfffff800
	s_nop 0
	global_load_lds_dwordx4 v160, s[64:65] offset:2048
	s_add_i32 m0, s76, 0xfffff800
	s_nop 0
	global_load_lds_dwordx4 v164, s[64:65] offset:2048
	s_waitcnt vmcnt(8)
	s_waitcnt lgkmcnt(0)
	s_setprio 1
	s_barrier
	v_mfma_f32_16x16x32_bf16 v[92:95], v[56:59], v[180:183], v[92:95]
	v_mfma_f32_16x16x32_bf16 v[88:91], v[64:67], v[180:183], v[88:91]
	v_mfma_f32_16x16x32_bf16 v[44:47], v[56:59], v[200:203], v[44:47]
	v_mfma_f32_16x16x32_bf16 v[40:43], v[64:67], v[200:203], v[40:43]
	v_mfma_f32_16x16x32_bf16 v[28:31], v[56:59], v[208:211], v[28:31]
	v_mfma_f32_16x16x32_bf16 v[24:27], v[64:67], v[208:211], v[24:27]
	v_mfma_f32_16x16x32_bf16 v[12:15], v[56:59], v[216:219], v[12:15]
	v_mfma_f32_16x16x32_bf16 v[8:11], v[64:67], v[216:219], v[8:11]
	v_mfma_f32_16x16x32_bf16 v[92:95], v[60:63], v[196:199], v[92:95]
	v_mfma_f32_16x16x32_bf16 v[88:91], v[68:71], v[196:199], v[88:91]
	v_mfma_f32_16x16x32_bf16 v[44:47], v[60:63], v[204:207], v[44:47]
	v_mfma_f32_16x16x32_bf16 v[40:43], v[68:71], v[204:207], v[40:43]
	v_mfma_f32_16x16x32_bf16 v[28:31], v[60:63], v[212:215], v[28:31]
	v_mfma_f32_16x16x32_bf16 v[24:27], v[68:71], v[212:215], v[24:27]
	v_mfma_f32_16x16x32_bf16 v[12:15], v[60:63], v[220:223], v[12:15]
	v_mfma_f32_16x16x32_bf16 v[8:11], v[68:71], v[220:223], v[8:11]
	v_mfma_f32_16x16x32_bf16 v[48:51], v[72:75], v[180:183], v[48:51]
	v_mfma_f32_16x16x32_bf16 v[52:55], v[80:83], v[180:183], v[52:55]
	v_mfma_f32_16x16x32_bf16 v[32:35], v[72:75], v[200:203], v[32:35]
	v_mfma_f32_16x16x32_bf16 v[36:39], v[80:83], v[200:203], v[36:39]
	v_mfma_f32_16x16x32_bf16 v[16:19], v[72:75], v[208:211], v[16:19]
	v_mfma_f32_16x16x32_bf16 v[20:23], v[80:83], v[208:211], v[20:23]
	v_mfma_f32_16x16x32_bf16 v[0:3], v[72:75], v[216:219], v[0:3]
	v_mfma_f32_16x16x32_bf16 v[4:7], v[80:83], v[216:219], v[4:7]
	v_mfma_f32_16x16x32_bf16 v[48:51], v[76:79], v[196:199], v[48:51]
	v_mfma_f32_16x16x32_bf16 v[68:71], v[84:87], v[196:199], v[52:55]
	v_mfma_f32_16x16x32_bf16 v[32:35], v[76:79], v[204:207], v[32:35]
	s_add_i32 s93, s93, 2
	v_mfma_f32_16x16x32_bf16 v[36:39], v[84:87], v[204:207], v[36:39]
	s_add_u32 s90, s90, 0x1000
	v_mfma_f32_16x16x32_bf16 v[16:19], v[76:79], v[212:215], v[16:19]
	s_addc_u32 s91, s91, 0
	v_mfma_f32_16x16x32_bf16 v[20:23], v[84:87], v[212:215], v[20:23]
	s_cmp_gt_u32 s93, 61
	v_mfma_f32_16x16x32_bf16 v[0:3], v[76:79], v[220:223], v[0:3]
	s_mov_b64 s[14:15], s[60:61]
	v_mfma_f32_16x16x32_bf16 v[4:7], v[84:87], v[220:223], v[4:7]
	s_barrier
	s_setprio 0
	s_cbranch_scc0 .LBB0_639
	s_and_b64 vcc, exec, s[42:43]
	s_cbranch_vccz .LBB0_642
	s_barrier

.LBB0_771:
	s_add_i32 m0, s44, 0xc000
	ds_read_b128 v[128:131], v188
	ds_read_b128 v[132:135], v188 offset:1024
	ds_read_b128 v[136:139], v188 offset:2048
	ds_read_b128 v[140:143], v188 offset:3072
	ds_read_b128 v[144:147], v189
	ds_read_b128 v[148:151], v189 offset:1024
	ds_read_b128 v[166:169], v189 offset:2048
	ds_read_b128 v[170:173], v189 offset:3072
	s_add_u32 s3, s38, 0xffd50800
	s_addc_u32 s16, s39, -1
	s_cmpk_eq_i32 s68, 0xa8
	s_cselect_b32 s43, s7, s16
	s_cselect_b32 s42, s6, s3
	s_cselect_b32 s41, s21, s67
	s_cselect_b32 s40, s20, s66
	ds_read_b128 v[174:177], v190
	ds_read_b128 v[178:181], v190 offset:1024
	ds_read_b128 v[182:185], v190 offset:2048
	ds_read_b128 v[196:199], v190 offset:3072
	ds_read_b128 v[200:203], v190 offset:4096
	ds_read_b128 v[204:207], v190 offset:5120
	ds_read_b128 v[208:211], v190 offset:6144
	ds_read_b128 v[212:215], v190 offset:7168
	global_load_lds_dwordx4 v158, s[38:39]
	s_add_i32 m0, s44, 0xe000
	s_nop 0
	global_load_lds_dwordx4 v160, s[38:39]
	s_waitcnt vmcnt(8)
	s_waitcnt lgkmcnt(0)
	s_setprio 1
	s_barrier
	v_mfma_f32_16x16x32_bf16 v[124:127], v[128:131], v[174:177], v[124:127]
	v_mfma_f32_16x16x32_bf16 v[120:123], v[136:139], v[174:177], v[120:123]
	v_mfma_f32_16x16x32_bf16 v[108:111], v[128:131], v[182:185], v[108:111]
	v_mfma_f32_16x16x32_bf16 v[104:107], v[136:139], v[182:185], v[104:107]
	v_mfma_f32_16x16x32_bf16 v[92:95], v[128:131], v[200:203], v[92:95]
	v_mfma_f32_16x16x32_bf16 v[88:91], v[136:139], v[200:203], v[88:91]
	v_mfma_f32_16x16x32_bf16 v[76:79], v[128:131], v[208:211], v[76:79]
	v_mfma_f32_16x16x32_bf16 v[72:75], v[136:139], v[208:211], v[72:75]
	v_mfma_f32_16x16x32_bf16 v[124:127], v[132:135], v[178:181], v[124:127]
	v_mfma_f32_16x16x32_bf16 v[120:123], v[140:143], v[178:181], v[120:123]
	v_mfma_f32_16x16x32_bf16 v[108:111], v[132:135], v[196:199], v[108:111]
	v_mfma_f32_16x16x32_bf16 v[104:107], v[140:143], v[196:199], v[104:107]
	v_mfma_f32_16x16x32_bf16 v[92:95], v[132:135], v[204:207], v[92:95]
	v_mfma_f32_16x16x32_bf16 v[88:91], v[140:143], v[204:207], v[88:91]
	v_mfma_f32_16x16x32_bf16 v[76:79], v[132:135], v[212:215], v[76:79]
	v_mfma_f32_16x16x32_bf16 v[72:75], v[140:143], v[212:215], v[72:75]
	v_mfma_f32_16x16x32_bf16 v[116:119], v[144:147], v[174:177], v[116:119]
	v_mfma_f32_16x16x32_bf16 v[112:115], v[166:169], v[174:177], v[112:115]
	v_mfma_f32_16x16x32_bf16 v[100:103], v[144:147], v[182:185], v[100:103]
	v_mfma_f32_16x16x32_bf16 v[96:99], v[166:169], v[182:185], v[96:99]
	v_mfma_f32_16x16x32_bf16 v[84:87], v[144:147], v[200:203], v[84:87]
	v_mfma_f32_16x16x32_bf16 v[80:83], v[166:169], v[200:203], v[80:83]
	v_mfma_f32_16x16x32_bf16 v[68:71], v[144:147], v[208:211], v[68:71]
	v_mfma_f32_16x16x32_bf16 v[64:67], v[166:169], v[208:211], v[64:67]
	v_mfma_f32_16x16x32_bf16 v[116:119], v[148:151], v[178:181], v[116:119]
	v_mfma_f32_16x16x32_bf16 v[112:115], v[170:173], v[178:181], v[112:115]
	v_mfma_f32_16x16x32_bf16 v[100:103], v[148:151], v[196:199], v[100:103]
	v_mfma_f32_16x16x32_bf16 v[96:99], v[170:173], v[196:199], v[96:99]
	v_mfma_f32_16x16x32_bf16 v[84:87], v[148:151], v[204:207], v[84:87]
	v_mfma_f32_16x16x32_bf16 v[80:83], v[170:173], v[204:207], v[80:83]
	v_mfma_f32_16x16x32_bf16 v[68:71], v[148:151], v[212:215], v[68:71]
	v_mfma_f32_16x16x32_bf16 v[64:67], v[170:173], v[212:215], v[64:67]
	s_barrier
	s_setprio 0
	s_add_i32 s3, s55, s19
	s_mov_b32 m0, s3
	ds_read_b128 v[174:177], v190 offset:16384
	ds_read_b128 v[178:181], v190 offset:17408
	ds_read_b128 v[182:185], v190 offset:18432
	ds_read_b128 v[196:199], v190 offset:19456
	ds_read_b128 v[200:203], v190 offset:20480
	ds_read_b128 v[204:207], v190 offset:21504
	ds_read_b128 v[208:211], v190 offset:22528
	ds_read_b128 v[212:215], v190 offset:23552
	global_load_lds_dwordx4 v152, s[40:41]
	s_add_i32 m0, s3, 0x2000
	s_add_u32 s16, s40, 0x2b0000
	s_addc_u32 s17, s41, 0
	global_load_lds_dwordx4 v154, s[40:41]
	s_add_i32 s3, s56, s19
	s_mov_b32 m0, s3
	s_nop 0
	global_load_lds_dwordx4 v152, s[16:17]
	s_add_i32 m0, s3, 0x2000
	s_nop 0
	global_load_lds_dwordx4 v154, s[16:17]
	s_mov_b32 m0, s44
	s_nop 0
	global_load_lds_dwordx4 v152, s[42:43]
	s_mov_b32 m0, s45
	s_nop 0
	global_load_lds_dwordx4 v154, s[42:43]
	s_waitcnt vmcnt(8)
	s_waitcnt lgkmcnt(0)
	s_setprio 1
	s_barrier
	v_mfma_f32_16x16x32_bf16 v[60:63], v[128:131], v[174:177], v[60:63]
	v_mfma_f32_16x16x32_bf16 v[56:59], v[136:139], v[174:177], v[56:59]
	v_mfma_f32_16x16x32_bf16 v[44:47], v[128:131], v[182:185], v[44:47]
	v_mfma_f32_16x16x32_bf16 v[40:43], v[136:139], v[182:185], v[40:43]
	v_mfma_f32_16x16x32_bf16 v[28:31], v[128:131], v[200:203], v[28:31]
	v_mfma_f32_16x16x32_bf16 v[24:27], v[136:139], v[200:203], v[24:27]
	v_mfma_f32_16x16x32_bf16 v[12:15], v[128:131], v[208:211], v[12:15]
	v_mfma_f32_16x16x32_bf16 v[8:11], v[136:139], v[208:211], v[8:11]
	v_mfma_f32_16x16x32_bf16 v[60:63], v[132:135], v[178:181], v[60:63]
	v_mfma_f32_16x16x32_bf16 v[56:59], v[140:143], v[178:181], v[56:59]
	v_mfma_f32_16x16x32_bf16 v[44:47], v[132:135], v[196:199], v[44:47]
	v_mfma_f32_16x16x32_bf16 v[40:43], v[140:143], v[196:199], v[40:43]
	v_mfma_f32_16x16x32_bf16 v[28:31], v[132:135], v[204:207], v[28:31]
	v_mfma_f32_16x16x32_bf16 v[24:27], v[140:143], v[204:207], v[24:27]
	v_mfma_f32_16x16x32_bf16 v[12:15], v[132:135], v[212:215], v[12:15]
	v_mfma_f32_16x16x32_bf16 v[8:11], v[140:143], v[212:215], v[8:11]
	v_mfma_f32_16x16x32_bf16 v[52:55], v[144:147], v[174:177], v[52:55]
	v_mfma_f32_16x16x32_bf16 v[48:51], v[166:169], v[174:177], v[48:51]
	v_mfma_f32_16x16x32_bf16 v[36:39], v[144:147], v[182:185], v[36:39]
	v_mfma_f32_16x16x32_bf16 v[32:35], v[166:169], v[182:185], v[32:35]
	v_mfma_f32_16x16x32_bf16 v[20:23], v[144:147], v[200:203], v[20:23]
	v_mfma_f32_16x16x32_bf16 v[16:19], v[166:169], v[200:203], v[16:19]
	v_mfma_f32_16x16x32_bf16 v[4:7], v[144:147], v[208:211], v[4:7]
	v_mfma_f32_16x16x32_bf16 v[0:3], v[166:169], v[208:211], v[0:3]
	v_mfma_f32_16x16x32_bf16 v[52:55], v[148:151], v[178:181], v[52:55]
	v_mfma_f32_16x16x32_bf16 v[48:51], v[170:173], v[178:181], v[48:51]
	v_mfma_f32_16x16x32_bf16 v[36:39], v[148:151], v[196:199], v[36:39]
	v_mfma_f32_16x16x32_bf16 v[32:35], v[170:173], v[196:199], v[32:35]
	v_mfma_f32_16x16x32_bf16 v[20:23], v[148:151], v[204:207], v[20:23]
	v_mfma_f32_16x16x32_bf16 v[16:19], v[170:173], v[204:207], v[16:19]
	v_mfma_f32_16x16x32_bf16 v[4:7], v[148:151], v[212:215], v[4:7]
	v_mfma_f32_16x16x32_bf16 v[0:3], v[170:173], v[212:215], v[0:3]
	s_barrier
	s_setprio 0
	s_add_i32 s3, 0, 0x18000
	s_add_i32 s33, 0, 0x1c000
	v_add_u32_e32 v140, s3, v187
	v_add_u32_e32 v170, s33, v187
	s_add_u32 s16, s42, 0x2b0000
	s_addc_u32 s17, s43, 0
	s_mov_b32 m0, s46
	ds_read_b128 v[128:131], v140
	ds_read_b128 v[132:135], v140 offset:1024
	ds_read_b128 v[136:139], v140 offset:2048
	ds_read_b128 v[140:143], v140 offset:3072
	ds_read_b128 v[144:147], v170
	ds_read_b128 v[148:151], v170 offset:1024
	ds_read_b128 v[166:169], v170 offset:2048
	ds_read_b128 v[170:173], v170 offset:3072
	ds_read_b128 v[174:177], v190 offset:32768
	ds_read_b128 v[178:181], v190 offset:33792
	ds_read_b128 v[182:185], v190 offset:34816
	ds_read_b128 v[196:199], v190 offset:35840
	ds_read_b128 v[200:203], v190 offset:36864
	ds_read_b128 v[204:207], v190 offset:37888
	ds_read_b128 v[208:211], v190 offset:38912
	ds_read_b128 v[212:215], v190 offset:39936
	global_load_lds_dwordx4 v152, s[16:17]
	s_mov_b32 m0, s47
	s_nop 0
	global_load_lds_dwordx4 v154, s[16:17]
	s_waitcnt vmcnt(8)
	s_waitcnt lgkmcnt(0)
	s_setprio 1
	s_barrier
	v_mfma_f32_16x16x32_bf16 v[124:127], v[128:131], v[174:177], v[124:127]
	v_mfma_f32_16x16x32_bf16 v[120:123], v[136:139], v[174:177], v[120:123]
	v_mfma_f32_16x16x32_bf16 v[108:111], v[128:131], v[182:185], v[108:111]
	v_mfma_f32_16x16x32_bf16 v[104:107], v[136:139], v[182:185], v[104:107]
	v_mfma_f32_16x16x32_bf16 v[92:95], v[128:131], v[200:203], v[92:95]
	v_mfma_f32_16x16x32_bf16 v[88:91], v[136:139], v[200:203], v[88:91]
	v_mfma_f32_16x16x32_bf16 v[76:79], v[128:131], v[208:211], v[76:79]
	v_mfma_f32_16x16x32_bf16 v[72:75], v[136:139], v[208:211], v[72:75]
	v_mfma_f32_16x16x32_bf16 v[124:127], v[132:135], v[178:181], v[124:127]
	v_mfma_f32_16x16x32_bf16 v[120:123], v[140:143], v[178:181], v[120:123]
	v_mfma_f32_16x16x32_bf16 v[108:111], v[132:135], v[196:199], v[108:111]
	v_mfma_f32_16x16x32_bf16 v[104:107], v[140:143], v[196:199], v[104:107]
	v_mfma_f32_16x16x32_bf16 v[92:95], v[132:135], v[204:207], v[92:95]
	v_mfma_f32_16x16x32_bf16 v[88:91], v[140:143], v[204:207], v[88:91]
	v_mfma_f32_16x16x32_bf16 v[76:79], v[132:135], v[212:215], v[76:79]
	v_mfma_f32_16x16x32_bf16 v[72:75], v[140:143], v[212:215], v[72:75]
	v_mfma_f32_16x16x32_bf16 v[116:119], v[144:147], v[174:177], v[116:119]
	v_mfma_f32_16x16x32_bf16 v[112:115], v[166:169], v[174:177], v[112:115]
	v_mfma_f32_16x16x32_bf16 v[100:103], v[144:147], v[182:185], v[100:103]
	v_mfma_f32_16x16x32_bf16 v[96:99], v[166:169], v[182:185], v[96:99]
	v_mfma_f32_16x16x32_bf16 v[84:87], v[144:147], v[200:203], v[84:87]
	v_mfma_f32_16x16x32_bf16 v[80:83], v[166:169], v[200:203], v[80:83]
	v_mfma_f32_16x16x32_bf16 v[68:71], v[144:147], v[208:211], v[68:71]
	v_mfma_f32_16x16x32_bf16 v[64:67], v[166:169], v[208:211], v[64:67]
	v_mfma_f32_16x16x32_bf16 v[116:119], v[148:151], v[178:181], v[116:119]
	v_mfma_f32_16x16x32_bf16 v[112:115], v[170:173], v[178:181], v[112:115]
	v_mfma_f32_16x16x32_bf16 v[100:103], v[148:151], v[196:199], v[100:103]
	v_mfma_f32_16x16x32_bf16 v[96:99], v[170:173], v[196:199], v[96:99]
	v_mfma_f32_16x16x32_bf16 v[84:87], v[148:151], v[204:207], v[84:87]
	v_mfma_f32_16x16x32_bf16 v[80:83], v[170:173], v[204:207], v[80:83]
	v_mfma_f32_16x16x32_bf16 v[68:71], v[148:151], v[212:215], v[68:71]
	v_mfma_f32_16x16x32_bf16 v[64:67], v[170:173], v[212:215], v[64:67]
	s_barrier
	s_setprio 0
	s_add_i32 m0, s19, 0x17800
	ds_read_b128 v[174:177], v190 offset:49152
	ds_read_b128 v[178:181], v190 offset:50176
	ds_read_b128 v[182:185], v190 offset:51200
	ds_read_b128 v[196:199], v190 offset:52224
	ds_read_b128 v[200:203], v190 offset:53248
	ds_read_b128 v[204:207], v190 offset:54272
	ds_read_b128 v[208:211], v190 offset:55296
	ds_read_b128 v[212:215], v190 offset:56320
	global_load_lds_dwordx4 v152, s[40:41] offset:2048
	s_add_i32 m0, s19, 0x19800
	s_add_u32 s16, s40, 0x2b0800
	s_addc_u32 s17, s41, 0
	global_load_lds_dwordx4 v154, s[40:41] offset:2048
	s_add_i32 m0, s19, 0x1c000
	s_nop 0
	global_load_lds_dwordx4 v152, s[16:17]
	s_add_i32 m0, s19, 0x1e000
	s_nop 0
	global_load_lds_dwordx4 v154, s[16:17]
	s_add_i32 m0, s50, 0xfffff800
	s_nop 0
	global_load_lds_dwordx4 v152, s[42:43] offset:2048
	s_add_i32 m0, s51, 0xfffff800
	s_nop 0
	global_load_lds_dwordx4 v154, s[42:43] offset:2048
	s_waitcnt vmcnt(8)
	s_waitcnt lgkmcnt(0)
	s_setprio 1
	s_barrier
	v_mfma_f32_16x16x32_bf16 v[60:63], v[128:131], v[174:177], v[60:63]
	v_mfma_f32_16x16x32_bf16 v[56:59], v[136:139], v[174:177], v[56:59]
	v_mfma_f32_16x16x32_bf16 v[44:47], v[128:131], v[182:185], v[44:47]
	v_mfma_f32_16x16x32_bf16 v[40:43], v[136:139], v[182:185], v[40:43]
	v_mfma_f32_16x16x32_bf16 v[28:31], v[128:131], v[200:203], v[28:31]
	v_mfma_f32_16x16x32_bf16 v[24:27], v[136:139], v[200:203], v[24:27]
	v_mfma_f32_16x16x32_bf16 v[12:15], v[128:131], v[208:211], v[12:15]
	v_mfma_f32_16x16x32_bf16 v[8:11], v[136:139], v[208:211], v[8:11]
	v_mfma_f32_16x16x32_bf16 v[60:63], v[132:135], v[178:181], v[60:63]
	v_mfma_f32_16x16x32_bf16 v[56:59], v[140:143], v[178:181], v[56:59]
	v_mfma_f32_16x16x32_bf16 v[44:47], v[132:135], v[196:199], v[44:47]
	v_mfma_f32_16x16x32_bf16 v[40:43], v[140:143], v[196:199], v[40:43]
	v_mfma_f32_16x16x32_bf16 v[28:31], v[132:135], v[204:207], v[28:31]
	v_mfma_f32_16x16x32_bf16 v[24:27], v[140:143], v[204:207], v[24:27]
	v_mfma_f32_16x16x32_bf16 v[12:15], v[132:135], v[212:215], v[12:15]
	v_mfma_f32_16x16x32_bf16 v[8:11], v[140:143], v[212:215], v[8:11]
	v_mfma_f32_16x16x32_bf16 v[52:55], v[144:147], v[174:177], v[52:55]
	v_mfma_f32_16x16x32_bf16 v[48:51], v[166:169], v[174:177], v[48:51]
	v_mfma_f32_16x16x32_bf16 v[36:39], v[144:147], v[182:185], v[36:39]
	v_mfma_f32_16x16x32_bf16 v[32:35], v[166:169], v[182:185], v[32:35]
	v_mfma_f32_16x16x32_bf16 v[20:23], v[144:147], v[200:203], v[20:23]
	v_mfma_f32_16x16x32_bf16 v[16:19], v[166:169], v[200:203], v[16:19]
	v_mfma_f32_16x16x32_bf16 v[4:7], v[144:147], v[208:211], v[4:7]
	v_mfma_f32_16x16x32_bf16 v[0:3], v[166:169], v[208:211], v[0:3]
	v_mfma_f32_16x16x32_bf16 v[52:55], v[148:151], v[178:181], v[52:55]
	v_mfma_f32_16x16x32_bf16 v[48:51], v[170:173], v[178:181], v[48:51]
	v_mfma_f32_16x16x32_bf16 v[36:39], v[148:151], v[196:199], v[36:39]
	s_add_i32 s68, s68, 2
	v_mfma_f32_16x16x32_bf16 v[32:35], v[170:173], v[196:199], v[32:35]
	s_add_u32 s38, s38, 0x1000
	v_mfma_f32_16x16x32_bf16 v[20:23], v[148:151], v[204:207], v[20:23]
	s_addc_u32 s39, s39, 0
	v_mfma_f32_16x16x32_bf16 v[16:19], v[170:173], v[204:207], v[16:19]
	s_add_u32 s66, s66, 0x1000
	v_mfma_f32_16x16x32_bf16 v[4:7], v[148:151], v[212:215], v[4:7]
	s_addc_u32 s67, s67, 0
	v_mfma_f32_16x16x32_bf16 v[0:3], v[170:173], v[212:215], v[0:3]
	s_cmpk_gt_u32 s68, 0xa9
	s_barrier
	s_setprio 0
	s_cbranch_scc0 .LBB0_771
	s_and_b64 vcc, exec, s[14:15]
	s_cbranch_vccz .LBB0_774
	s_barrier
